# v7 shifted by 32 bytes (8 s_nop at entry): code placement check
# speedup vs baseline: 1.0071x; 1.0052x over previous
_Z6mk_fwd4Args:
	s_nop 0
	s_nop 0
	s_nop 0
	s_nop 0
	s_nop 0
	s_nop 0
	s_nop 0
	s_nop 0
	s_load_dwordx8 s[4:11], s[0:1], 0x80
	v_mov_b32_e32 v1, v0
	s_mov_b32 s81, s2
	s_add_u32 s2, s0, 0xb8
	s_waitcnt lgkmcnt(0)
	v_writelane_b32 v251, s4, 0
	s_addc_u32 s3, s1, 0
	s_nop 0
	v_writelane_b32 v251, s5, 1
	v_writelane_b32 v251, s6, 2
	v_writelane_b32 v251, s7, 3
	v_writelane_b32 v251, s8, 4
	v_writelane_b32 v251, s9, 5
	v_writelane_b32 v251, s10, 6
	v_writelane_b32 v251, s11, 7
	s_load_dword s82, s[0:1], 0xb8
	s_load_dwordx2 s[94:95], s[0:1], 0xa0
	s_load_dwordx4 s[4:7], s[0:1], 0xa8
	s_waitcnt lgkmcnt(0)
	v_writelane_b32 v251, s4, 8
	s_nop 1
	v_writelane_b32 v251, s5, 9
	v_writelane_b32 v251, s6, 10
	v_writelane_b32 v251, s7, 11
	v_writelane_b32 v251, s2, 12
	v_readfirstlane_b32 s6, v1
	s_mov_b32 s7, s81
	v_writelane_b32 v251, s3, 13
	s_and_b32 s2, s82, 7
	s_cmp_lg_u32 s2, 0
	s_cbranch_scc0 .LBB0_2
	s_movk_i32 s2, 0x400
	v_cmp_gt_i32_e32 vcc, s2, v1
	s_and_saveexec_b64 s[2:3], vcc
	s_cbranch_execnz .LBB0_3
	s_branch .LBB0_5
